# speedup vs baseline: 1.0114x; 1.0114x over previous
; DEVI int lbid() { int t = blockIdx.x; asm volatile("" : "+s"(t)); return t; }
; DEVI int lgdim() { int t = gridDim.x; asm volatile("" : "+s"(t)); return t; }
; DEVI float bflo(unsigned u) { return __uint_as_float(u << 16); }
; DEVI float bfhi(unsigned u) { return __uint_as_float(u & 0xffff0000u); }
; DEVI void lru_p1_phase(const Params& p) {
;     ...
;   for (int it = lbid(); it < 4 * NCH64B; it += lgdim()) {
;     const int pos = it % NCH64B, db = it / NCH64B, dir = db >> 1, b = db & 1;
;     const int c = lru_chunk_of_pos(dir, pos), rbase = lru_rowbase(b, c);
;     const bf16_t* la = LA + ((size_t)dir * MT + rbase) * 1024 + ch; const bf16_t* bb = BB + ((size_t)dir * MT + rbase) * 1024 + ch;
;     float h0 = 0.f, P0 = 0.f, h1 = 0.f, P1 = 0.f;
; #pragma unroll 16
;     for (int t = 0; t < 64; ++t) {
;       const int rr = dir == 0 ? t : 63 - t;
;       const unsigned l = *(const unsigned*)(la + (size_t)rr * 1024), bv = *(const unsigned*)(bb + (size_t)rr * 1024);
;       h0 = __expf(bflo(l)) * h0 + bflo(bv); P0 += bflo(l); h1 = __expf(bfhi(l)) * h1 + bfhi(bv); P1 += bfhi(l);
.LBB0_1145:
	s_ashr_i32 s16, s22, 1
	s_mul_hi_i32 s17, s16, 0x8200
	s_mul_i32 s16, s16, 0x8200
	s_add_u32 s16, s16, s34
	s_addc_u32 s17, s17, 0
	s_lshl_b64 s[16:17], s[16:17], 11
	v_mov_b32_e32 v12, 0
	v_lshl_add_u64 v[8:9], v[4:5], 0, s[16:17]
	v_lshl_add_u64 v[10:11], v[6:7], 0, s[16:17]
	v_mov_b32_e32 v13, v12
	v_mov_b32_e32 v14, v12
	v_mov_b32_e32 v15, v12
	s_and_b64 s[24:25], s[14:15], exec
	s_mov_b32 s35, 0xfffff800
	s_and_b64 s[24:25], s[14:15], exec
	s_cselect_b32 s34, 0x800, s35
	s_cselect_b32 s80, 0, 0x1f800
	s_mov_b32 s16, 2
.Llp1_chunk:
	v_lshl_add_u64 v[16:17], v[8:9], 0, s[80:81]
	global_load_dword v22, v[16:17], off
	v_lshl_add_u64 v[16:17], v[10:11], 0, s[80:81]
	global_load_dword v54, v[16:17], off
	s_add_i32 s80, s80, s34
	v_lshl_add_u64 v[16:17], v[8:9], 0, s[80:81]
	global_load_dword v23, v[16:17], off
	v_lshl_add_u64 v[16:17], v[10:11], 0, s[80:81]
	global_load_dword v55, v[16:17], off
	s_add_i32 s80, s80, s34
	v_lshl_add_u64 v[16:17], v[8:9], 0, s[80:81]
	global_load_dword v24, v[16:17], off
	v_lshl_add_u64 v[16:17], v[10:11], 0, s[80:81]
	global_load_dword v56, v[16:17], off
	s_add_i32 s80, s80, s34
	v_lshl_add_u64 v[16:17], v[8:9], 0, s[80:81]
	global_load_dword v25, v[16:17], off
	v_lshl_add_u64 v[16:17], v[10:11], 0, s[80:81]
	global_load_dword v57, v[16:17], off
	s_add_i32 s80, s80, s34
	v_lshl_add_u64 v[16:17], v[8:9], 0, s[80:81]
	global_load_dword v26, v[16:17], off
	v_lshl_add_u64 v[16:17], v[10:11], 0, s[80:81]
	global_load_dword v58, v[16:17], off
	s_add_i32 s80, s80, s34
	v_lshl_add_u64 v[16:17], v[8:9], 0, s[80:81]
	global_load_dword v27, v[16:17], off
	v_lshl_add_u64 v[16:17], v[10:11], 0, s[80:81]
	global_load_dword v59, v[16:17], off
	s_add_i32 s80, s80, s34
	v_lshl_add_u64 v[16:17], v[8:9], 0, s[80:81]
	global_load_dword v28, v[16:17], off
	v_lshl_add_u64 v[16:17], v[10:11], 0, s[80:81]
	global_load_dword v60, v[16:17], off
	s_add_i32 s80, s80, s34
	v_lshl_add_u64 v[16:17], v[8:9], 0, s[80:81]
	global_load_dword v29, v[16:17], off
	v_lshl_add_u64 v[16:17], v[10:11], 0, s[80:81]
	global_load_dword v61, v[16:17], off
	s_add_i32 s80, s80, s34
	v_lshl_add_u64 v[16:17], v[8:9], 0, s[80:81]
	global_load_dword v30, v[16:17], off
	v_lshl_add_u64 v[16:17], v[10:11], 0, s[80:81]
	global_load_dword v62, v[16:17], off
	s_add_i32 s80, s80, s34
	v_lshl_add_u64 v[16:17], v[8:9], 0, s[80:81]
	global_load_dword v31, v[16:17], off
	v_lshl_add_u64 v[16:17], v[10:11], 0, s[80:81]
	global_load_dword v63, v[16:17], off
	s_add_i32 s80, s80, s34
	v_lshl_add_u64 v[16:17], v[8:9], 0, s[80:81]
	global_load_dword v32, v[16:17], off
	v_lshl_add_u64 v[16:17], v[10:11], 0, s[80:81]
	global_load_dword v64, v[16:17], off
	s_add_i32 s80, s80, s34
	v_lshl_add_u64 v[16:17], v[8:9], 0, s[80:81]
	global_load_dword v33, v[16:17], off
	v_lshl_add_u64 v[16:17], v[10:11], 0, s[80:81]
	global_load_dword v65, v[16:17], off
	s_add_i32 s80, s80, s34
	v_lshl_add_u64 v[16:17], v[8:9], 0, s[80:81]
	global_load_dword v34, v[16:17], off
	v_lshl_add_u64 v[16:17], v[10:11], 0, s[80:81]
	global_load_dword v66, v[16:17], off
	s_add_i32 s80, s80, s34
	v_lshl_add_u64 v[16:17], v[8:9], 0, s[80:81]
	global_load_dword v35, v[16:17], off
	v_lshl_add_u64 v[16:17], v[10:11], 0, s[80:81]
	global_load_dword v67, v[16:17], off
	s_add_i32 s80, s80, s34
	v_lshl_add_u64 v[16:17], v[8:9], 0, s[80:81]
	global_load_dword v36, v[16:17], off
	v_lshl_add_u64 v[16:17], v[10:11], 0, s[80:81]
	global_load_dword v68, v[16:17], off
	s_add_i32 s80, s80, s34
	v_lshl_add_u64 v[16:17], v[8:9], 0, s[80:81]
	global_load_dword v37, v[16:17], off
	v_lshl_add_u64 v[16:17], v[10:11], 0, s[80:81]
	global_load_dword v69, v[16:17], off
	s_add_i32 s80, s80, s34
	v_lshl_add_u64 v[16:17], v[8:9], 0, s[80:81]
	global_load_dword v38, v[16:17], off
	v_lshl_add_u64 v[16:17], v[10:11], 0, s[80:81]
	global_load_dword v70, v[16:17], off
	s_add_i32 s80, s80, s34
	v_lshl_add_u64 v[16:17], v[8:9], 0, s[80:81]
	global_load_dword v39, v[16:17], off
	v_lshl_add_u64 v[16:17], v[10:11], 0, s[80:81]
	global_load_dword v71, v[16:17], off
	s_add_i32 s80, s80, s34
	v_lshl_add_u64 v[16:17], v[8:9], 0, s[80:81]
	global_load_dword v40, v[16:17], off
	v_lshl_add_u64 v[16:17], v[10:11], 0, s[80:81]
	global_load_dword v72, v[16:17], off
	s_add_i32 s80, s80, s34
	v_lshl_add_u64 v[16:17], v[8:9], 0, s[80:81]
	global_load_dword v41, v[16:17], off
	v_lshl_add_u64 v[16:17], v[10:11], 0, s[80:81]
	global_load_dword v73, v[16:17], off
	s_add_i32 s80, s80, s34
	v_lshl_add_u64 v[16:17], v[8:9], 0, s[80:81]
	global_load_dword v42, v[16:17], off
	v_lshl_add_u64 v[16:17], v[10:11], 0, s[80:81]
	global_load_dword v74, v[16:17], off
	s_add_i32 s80, s80, s34
	v_lshl_add_u64 v[16:17], v[8:9], 0, s[80:81]
	global_load_dword v43, v[16:17], off
	v_lshl_add_u64 v[16:17], v[10:11], 0, s[80:81]
	global_load_dword v75, v[16:17], off
	s_add_i32 s80, s80, s34
	v_lshl_add_u64 v[16:17], v[8:9], 0, s[80:81]
	global_load_dword v44, v[16:17], off
	v_lshl_add_u64 v[16:17], v[10:11], 0, s[80:81]
	global_load_dword v76, v[16:17], off
	s_add_i32 s80, s80, s34
	v_lshl_add_u64 v[16:17], v[8:9], 0, s[80:81]
	global_load_dword v45, v[16:17], off
	v_lshl_add_u64 v[16:17], v[10:11], 0, s[80:81]
	global_load_dword v77, v[16:17], off
	s_add_i32 s80, s80, s34
	v_lshl_add_u64 v[16:17], v[8:9], 0, s[80:81]
	global_load_dword v46, v[16:17], off
	v_lshl_add_u64 v[16:17], v[10:11], 0, s[80:81]
	global_load_dword v78, v[16:17], off
	s_add_i32 s80, s80, s34
	v_lshl_add_u64 v[16:17], v[8:9], 0, s[80:81]
	global_load_dword v47, v[16:17], off
	v_lshl_add_u64 v[16:17], v[10:11], 0, s[80:81]
	global_load_dword v79, v[16:17], off
	s_add_i32 s80, s80, s34
	v_lshl_add_u64 v[16:17], v[8:9], 0, s[80:81]
	global_load_dword v48, v[16:17], off
	v_lshl_add_u64 v[16:17], v[10:11], 0, s[80:81]
	global_load_dword v80, v[16:17], off
	s_add_i32 s80, s80, s34
	v_lshl_add_u64 v[16:17], v[8:9], 0, s[80:81]
	global_load_dword v49, v[16:17], off
	v_lshl_add_u64 v[16:17], v[10:11], 0, s[80:81]
	global_load_dword v81, v[16:17], off
	s_add_i32 s80, s80, s34
	v_lshl_add_u64 v[16:17], v[8:9], 0, s[80:81]
	global_load_dword v50, v[16:17], off
	v_lshl_add_u64 v[16:17], v[10:11], 0, s[80:81]
	global_load_dword v82, v[16:17], off
	s_add_i32 s80, s80, s34
	v_lshl_add_u64 v[16:17], v[8:9], 0, s[80:81]
	global_load_dword v51, v[16:17], off
	v_lshl_add_u64 v[16:17], v[10:11], 0, s[80:81]
	global_load_dword v83, v[16:17], off
	s_add_i32 s80, s80, s34
	v_lshl_add_u64 v[16:17], v[8:9], 0, s[80:81]
	global_load_dword v52, v[16:17], off
	v_lshl_add_u64 v[16:17], v[10:11], 0, s[80:81]
	global_load_dword v84, v[16:17], off
	s_add_i32 s80, s80, s34
	v_lshl_add_u64 v[16:17], v[8:9], 0, s[80:81]
	global_load_dword v53, v[16:17], off
	v_lshl_add_u64 v[16:17], v[10:11], 0, s[80:81]
	global_load_dword v85, v[16:17], off
	s_add_i32 s80, s80, s34
	s_waitcnt vmcnt(63)
; DEVI float bflo(unsigned u) { return __uint_as_float(u << 16); }
; DEVI float bfhi(unsigned u) { return __uint_as_float(u & 0xffff0000u); }
; DEVI void lru_p1_phase(const Params& p) {
;     ...
;     for (int t = 0; t < 64; ++t) {
;       const int rr = dir == 0 ? t : 63 - t;
;       const unsigned l = *(const unsigned*)(la + (size_t)rr * 1024), bv = *(const unsigned*)(bb + (size_t)rr * 1024);
;       h0 = __expf(bflo(l)) * h0 + bflo(bv); P0 += bflo(l); h1 = __expf(bfhi(l)) * h1 + bfhi(bv); P1 += bfhi(l);
	v_lshlrev_b32_e32 v16, 16, v22
	v_and_b32_e32 v17, 0xffff0000, v22
	v_mul_f32_e32 v0, 0x3fb8aa3b, v16
	v_exp_f32_e32 v20, v0
	v_mul_f32_e32 v0, 0x3fb8aa3b, v17
	v_pk_add_f32 v[12:13], v[12:13], v[16:17]
	v_exp_f32_e32 v21, v0
	s_waitcnt vmcnt(62)
	v_lshlrev_b32_e32 v18, 16, v54
	v_and_b32_e32 v19, 0xffff0000, v54
	v_pk_fma_f32 v[14:15], v[14:15], v[20:21], v[18:19]
	s_waitcnt vmcnt(61)
	v_lshlrev_b32_e32 v16, 16, v23
	v_and_b32_e32 v17, 0xffff0000, v23
	v_mul_f32_e32 v0, 0x3fb8aa3b, v16
	v_exp_f32_e32 v20, v0
	v_mul_f32_e32 v0, 0x3fb8aa3b, v17
	v_pk_add_f32 v[12:13], v[12:13], v[16:17]
	v_exp_f32_e32 v21, v0
	s_waitcnt vmcnt(60)
	v_lshlrev_b32_e32 v18, 16, v55
	v_and_b32_e32 v19, 0xffff0000, v55
	v_pk_fma_f32 v[14:15], v[14:15], v[20:21], v[18:19]
	s_waitcnt vmcnt(59)
	v_lshlrev_b32_e32 v16, 16, v24
	v_and_b32_e32 v17, 0xffff0000, v24
	v_mul_f32_e32 v0, 0x3fb8aa3b, v16
	v_exp_f32_e32 v20, v0
	v_mul_f32_e32 v0, 0x3fb8aa3b, v17
	v_pk_add_f32 v[12:13], v[12:13], v[16:17]
	v_exp_f32_e32 v21, v0
	s_waitcnt vmcnt(58)
	v_lshlrev_b32_e32 v18, 16, v56
	v_and_b32_e32 v19, 0xffff0000, v56
	v_pk_fma_f32 v[14:15], v[14:15], v[20:21], v[18:19]
	s_waitcnt vmcnt(57)
	v_lshlrev_b32_e32 v16, 16, v25
	v_and_b32_e32 v17, 0xffff0000, v25
	v_mul_f32_e32 v0, 0x3fb8aa3b, v16
	v_exp_f32_e32 v20, v0
	v_mul_f32_e32 v0, 0x3fb8aa3b, v17
	v_pk_add_f32 v[12:13], v[12:13], v[16:17]
	v_exp_f32_e32 v21, v0
	s_waitcnt vmcnt(56)
	v_lshlrev_b32_e32 v18, 16, v57
	v_and_b32_e32 v19, 0xffff0000, v57
	v_pk_fma_f32 v[14:15], v[14:15], v[20:21], v[18:19]
	s_waitcnt vmcnt(55)
	v_lshlrev_b32_e32 v16, 16, v26
	v_and_b32_e32 v17, 0xffff0000, v26
	v_mul_f32_e32 v0, 0x3fb8aa3b, v16
	v_exp_f32_e32 v20, v0
	v_mul_f32_e32 v0, 0x3fb8aa3b, v17
	v_pk_add_f32 v[12:13], v[12:13], v[16:17]
	v_exp_f32_e32 v21, v0
	s_waitcnt vmcnt(54)
	v_lshlrev_b32_e32 v18, 16, v58
	v_and_b32_e32 v19, 0xffff0000, v58
	v_pk_fma_f32 v[14:15], v[14:15], v[20:21], v[18:19]
	s_waitcnt vmcnt(53)
	v_lshlrev_b32_e32 v16, 16, v27
	v_and_b32_e32 v17, 0xffff0000, v27
	v_mul_f32_e32 v0, 0x3fb8aa3b, v16
	v_exp_f32_e32 v20, v0
	v_mul_f32_e32 v0, 0x3fb8aa3b, v17
	v_pk_add_f32 v[12:13], v[12:13], v[16:17]
	v_exp_f32_e32 v21, v0
	s_waitcnt vmcnt(52)
	v_lshlrev_b32_e32 v18, 16, v59
	v_and_b32_e32 v19, 0xffff0000, v59
	v_pk_fma_f32 v[14:15], v[14:15], v[20:21], v[18:19]
	s_waitcnt vmcnt(51)
	v_lshlrev_b32_e32 v16, 16, v28
	v_and_b32_e32 v17, 0xffff0000, v28
	v_mul_f32_e32 v0, 0x3fb8aa3b, v16
	v_exp_f32_e32 v20, v0
	v_mul_f32_e32 v0, 0x3fb8aa3b, v17
	v_pk_add_f32 v[12:13], v[12:13], v[16:17]
	v_exp_f32_e32 v21, v0
	s_waitcnt vmcnt(50)
	v_lshlrev_b32_e32 v18, 16, v60
	v_and_b32_e32 v19, 0xffff0000, v60
	v_pk_fma_f32 v[14:15], v[14:15], v[20:21], v[18:19]
	s_waitcnt vmcnt(49)
	v_lshlrev_b32_e32 v16, 16, v29
	v_and_b32_e32 v17, 0xffff0000, v29
	v_mul_f32_e32 v0, 0x3fb8aa3b, v16
	v_exp_f32_e32 v20, v0
	v_mul_f32_e32 v0, 0x3fb8aa3b, v17
	v_pk_add_f32 v[12:13], v[12:13], v[16:17]
	v_exp_f32_e32 v21, v0
	s_waitcnt vmcnt(48)
	v_lshlrev_b32_e32 v18, 16, v61
	v_and_b32_e32 v19, 0xffff0000, v61
	v_pk_fma_f32 v[14:15], v[14:15], v[20:21], v[18:19]
	s_waitcnt vmcnt(47)
	v_lshlrev_b32_e32 v16, 16, v30
	v_and_b32_e32 v17, 0xffff0000, v30
	v_mul_f32_e32 v0, 0x3fb8aa3b, v16
	v_exp_f32_e32 v20, v0
	v_mul_f32_e32 v0, 0x3fb8aa3b, v17
	v_pk_add_f32 v[12:13], v[12:13], v[16:17]
	v_exp_f32_e32 v21, v0
	s_waitcnt vmcnt(46)
	v_lshlrev_b32_e32 v18, 16, v62
	v_and_b32_e32 v19, 0xffff0000, v62
	v_pk_fma_f32 v[14:15], v[14:15], v[20:21], v[18:19]
	s_waitcnt vmcnt(45)
	v_lshlrev_b32_e32 v16, 16, v31
	v_and_b32_e32 v17, 0xffff0000, v31
	v_mul_f32_e32 v0, 0x3fb8aa3b, v16
	v_exp_f32_e32 v20, v0
	v_mul_f32_e32 v0, 0x3fb8aa3b, v17
	v_pk_add_f32 v[12:13], v[12:13], v[16:17]
	v_exp_f32_e32 v21, v0
	s_waitcnt vmcnt(44)
	v_lshlrev_b32_e32 v18, 16, v63
	v_and_b32_e32 v19, 0xffff0000, v63
	v_pk_fma_f32 v[14:15], v[14:15], v[20:21], v[18:19]
	s_waitcnt vmcnt(43)
	v_lshlrev_b32_e32 v16, 16, v32
	v_and_b32_e32 v17, 0xffff0000, v32
	v_mul_f32_e32 v0, 0x3fb8aa3b, v16
	v_exp_f32_e32 v20, v0
	v_mul_f32_e32 v0, 0x3fb8aa3b, v17
	v_pk_add_f32 v[12:13], v[12:13], v[16:17]
	v_exp_f32_e32 v21, v0
	s_waitcnt vmcnt(42)
	v_lshlrev_b32_e32 v18, 16, v64
	v_and_b32_e32 v19, 0xffff0000, v64
	v_pk_fma_f32 v[14:15], v[14:15], v[20:21], v[18:19]
	s_waitcnt vmcnt(41)
	v_lshlrev_b32_e32 v16, 16, v33
	v_and_b32_e32 v17, 0xffff0000, v33
	v_mul_f32_e32 v0, 0x3fb8aa3b, v16
	v_exp_f32_e32 v20, v0
	v_mul_f32_e32 v0, 0x3fb8aa3b, v17
	v_pk_add_f32 v[12:13], v[12:13], v[16:17]
	v_exp_f32_e32 v21, v0
	s_waitcnt vmcnt(40)
	v_lshlrev_b32_e32 v18, 16, v65
	v_and_b32_e32 v19, 0xffff0000, v65
	v_pk_fma_f32 v[14:15], v[14:15], v[20:21], v[18:19]
	s_waitcnt vmcnt(39)
	v_lshlrev_b32_e32 v16, 16, v34
	v_and_b32_e32 v17, 0xffff0000, v34
	v_mul_f32_e32 v0, 0x3fb8aa3b, v16
	v_exp_f32_e32 v20, v0
	v_mul_f32_e32 v0, 0x3fb8aa3b, v17
	v_pk_add_f32 v[12:13], v[12:13], v[16:17]
	v_exp_f32_e32 v21, v0
	s_waitcnt vmcnt(38)
	v_lshlrev_b32_e32 v18, 16, v66
	v_and_b32_e32 v19, 0xffff0000, v66
	v_pk_fma_f32 v[14:15], v[14:15], v[20:21], v[18:19]
	s_waitcnt vmcnt(37)
	v_lshlrev_b32_e32 v16, 16, v35
	v_and_b32_e32 v17, 0xffff0000, v35
	v_mul_f32_e32 v0, 0x3fb8aa3b, v16
	v_exp_f32_e32 v20, v0
	v_mul_f32_e32 v0, 0x3fb8aa3b, v17
	v_pk_add_f32 v[12:13], v[12:13], v[16:17]
	v_exp_f32_e32 v21, v0
	s_waitcnt vmcnt(36)
	v_lshlrev_b32_e32 v18, 16, v67
	v_and_b32_e32 v19, 0xffff0000, v67
	v_pk_fma_f32 v[14:15], v[14:15], v[20:21], v[18:19]
	s_waitcnt vmcnt(35)
	v_lshlrev_b32_e32 v16, 16, v36
	v_and_b32_e32 v17, 0xffff0000, v36
	v_mul_f32_e32 v0, 0x3fb8aa3b, v16
	v_exp_f32_e32 v20, v0
	v_mul_f32_e32 v0, 0x3fb8aa3b, v17
	v_pk_add_f32 v[12:13], v[12:13], v[16:17]
	v_exp_f32_e32 v21, v0
	s_waitcnt vmcnt(34)
; DEVI float bflo(unsigned u) { return __uint_as_float(u << 16); }
; DEVI float bfhi(unsigned u) { return __uint_as_float(u & 0xffff0000u); }
; DEVI void lru_p1_phase(const Params& p) {
;     ...
;     for (int t = 0; t < 64; ++t) {
;       const int rr = dir == 0 ? t : 63 - t;
;       const unsigned l = *(const unsigned*)(la + (size_t)rr * 1024), bv = *(const unsigned*)(bb + (size_t)rr * 1024);
;       h0 = __expf(bflo(l)) * h0 + bflo(bv); P0 += bflo(l); h1 = __expf(bfhi(l)) * h1 + bfhi(bv); P1 += bfhi(l);
	v_lshlrev_b32_e32 v18, 16, v68
	v_and_b32_e32 v19, 0xffff0000, v68
	v_pk_fma_f32 v[14:15], v[14:15], v[20:21], v[18:19]
	s_waitcnt vmcnt(33)
	v_lshlrev_b32_e32 v16, 16, v37
	v_and_b32_e32 v17, 0xffff0000, v37
	v_mul_f32_e32 v0, 0x3fb8aa3b, v16
	v_exp_f32_e32 v20, v0
	v_mul_f32_e32 v0, 0x3fb8aa3b, v17
	v_pk_add_f32 v[12:13], v[12:13], v[16:17]
	v_exp_f32_e32 v21, v0
	s_waitcnt vmcnt(32)
	v_lshlrev_b32_e32 v18, 16, v69
	v_and_b32_e32 v19, 0xffff0000, v69
	v_pk_fma_f32 v[14:15], v[14:15], v[20:21], v[18:19]
	s_waitcnt vmcnt(31)
	v_lshlrev_b32_e32 v16, 16, v38
	v_and_b32_e32 v17, 0xffff0000, v38
	v_mul_f32_e32 v0, 0x3fb8aa3b, v16
	v_exp_f32_e32 v20, v0
	v_mul_f32_e32 v0, 0x3fb8aa3b, v17
	v_pk_add_f32 v[12:13], v[12:13], v[16:17]
	v_exp_f32_e32 v21, v0
	s_waitcnt vmcnt(30)
	v_lshlrev_b32_e32 v18, 16, v70
	v_and_b32_e32 v19, 0xffff0000, v70
	v_pk_fma_f32 v[14:15], v[14:15], v[20:21], v[18:19]
	s_waitcnt vmcnt(29)
	v_lshlrev_b32_e32 v16, 16, v39
	v_and_b32_e32 v17, 0xffff0000, v39
	v_mul_f32_e32 v0, 0x3fb8aa3b, v16
	v_exp_f32_e32 v20, v0
	v_mul_f32_e32 v0, 0x3fb8aa3b, v17
	v_pk_add_f32 v[12:13], v[12:13], v[16:17]
	v_exp_f32_e32 v21, v0
	s_waitcnt vmcnt(28)
	v_lshlrev_b32_e32 v18, 16, v71
	v_and_b32_e32 v19, 0xffff0000, v71
	v_pk_fma_f32 v[14:15], v[14:15], v[20:21], v[18:19]
	s_waitcnt vmcnt(27)
	v_lshlrev_b32_e32 v16, 16, v40
	v_and_b32_e32 v17, 0xffff0000, v40
	v_mul_f32_e32 v0, 0x3fb8aa3b, v16
	v_exp_f32_e32 v20, v0
	v_mul_f32_e32 v0, 0x3fb8aa3b, v17
	v_pk_add_f32 v[12:13], v[12:13], v[16:17]
	v_exp_f32_e32 v21, v0
	s_waitcnt vmcnt(26)
	v_lshlrev_b32_e32 v18, 16, v72
	v_and_b32_e32 v19, 0xffff0000, v72
	v_pk_fma_f32 v[14:15], v[14:15], v[20:21], v[18:19]
	s_waitcnt vmcnt(25)
	v_lshlrev_b32_e32 v16, 16, v41
	v_and_b32_e32 v17, 0xffff0000, v41
	v_mul_f32_e32 v0, 0x3fb8aa3b, v16
	v_exp_f32_e32 v20, v0
	v_mul_f32_e32 v0, 0x3fb8aa3b, v17
	v_pk_add_f32 v[12:13], v[12:13], v[16:17]
	v_exp_f32_e32 v21, v0
	s_waitcnt vmcnt(24)
	v_lshlrev_b32_e32 v18, 16, v73
	v_and_b32_e32 v19, 0xffff0000, v73
	v_pk_fma_f32 v[14:15], v[14:15], v[20:21], v[18:19]
	s_waitcnt vmcnt(23)
	v_lshlrev_b32_e32 v16, 16, v42
	v_and_b32_e32 v17, 0xffff0000, v42
	v_mul_f32_e32 v0, 0x3fb8aa3b, v16
	v_exp_f32_e32 v20, v0
	v_mul_f32_e32 v0, 0x3fb8aa3b, v17
	v_pk_add_f32 v[12:13], v[12:13], v[16:17]
	v_exp_f32_e32 v21, v0
	s_waitcnt vmcnt(22)
	v_lshlrev_b32_e32 v18, 16, v74
	v_and_b32_e32 v19, 0xffff0000, v74
	v_pk_fma_f32 v[14:15], v[14:15], v[20:21], v[18:19]
	s_waitcnt vmcnt(21)
	v_lshlrev_b32_e32 v16, 16, v43
	v_and_b32_e32 v17, 0xffff0000, v43
	v_mul_f32_e32 v0, 0x3fb8aa3b, v16
	v_exp_f32_e32 v20, v0
	v_mul_f32_e32 v0, 0x3fb8aa3b, v17
	v_pk_add_f32 v[12:13], v[12:13], v[16:17]
	v_exp_f32_e32 v21, v0
	s_waitcnt vmcnt(20)
	v_lshlrev_b32_e32 v18, 16, v75
	v_and_b32_e32 v19, 0xffff0000, v75
	v_pk_fma_f32 v[14:15], v[14:15], v[20:21], v[18:19]
	s_waitcnt vmcnt(19)
	v_lshlrev_b32_e32 v16, 16, v44
	v_and_b32_e32 v17, 0xffff0000, v44
	v_mul_f32_e32 v0, 0x3fb8aa3b, v16
	v_exp_f32_e32 v20, v0
	v_mul_f32_e32 v0, 0x3fb8aa3b, v17
	v_pk_add_f32 v[12:13], v[12:13], v[16:17]
	v_exp_f32_e32 v21, v0
	s_waitcnt vmcnt(18)
	v_lshlrev_b32_e32 v18, 16, v76
	v_and_b32_e32 v19, 0xffff0000, v76
	v_pk_fma_f32 v[14:15], v[14:15], v[20:21], v[18:19]
	s_waitcnt vmcnt(17)
	v_lshlrev_b32_e32 v16, 16, v45
	v_and_b32_e32 v17, 0xffff0000, v45
	v_mul_f32_e32 v0, 0x3fb8aa3b, v16
	v_exp_f32_e32 v20, v0
	v_mul_f32_e32 v0, 0x3fb8aa3b, v17
	v_pk_add_f32 v[12:13], v[12:13], v[16:17]
	v_exp_f32_e32 v21, v0
	s_waitcnt vmcnt(16)
	v_lshlrev_b32_e32 v18, 16, v77
	v_and_b32_e32 v19, 0xffff0000, v77
	v_pk_fma_f32 v[14:15], v[14:15], v[20:21], v[18:19]
	s_waitcnt vmcnt(15)
	v_lshlrev_b32_e32 v16, 16, v46
	v_and_b32_e32 v17, 0xffff0000, v46
	v_mul_f32_e32 v0, 0x3fb8aa3b, v16
	v_exp_f32_e32 v20, v0
	v_mul_f32_e32 v0, 0x3fb8aa3b, v17
	v_pk_add_f32 v[12:13], v[12:13], v[16:17]
	v_exp_f32_e32 v21, v0
	s_waitcnt vmcnt(14)
	v_lshlrev_b32_e32 v18, 16, v78
	v_and_b32_e32 v19, 0xffff0000, v78
	v_pk_fma_f32 v[14:15], v[14:15], v[20:21], v[18:19]
	s_waitcnt vmcnt(13)
	v_lshlrev_b32_e32 v16, 16, v47
	v_and_b32_e32 v17, 0xffff0000, v47
	v_mul_f32_e32 v0, 0x3fb8aa3b, v16
	v_exp_f32_e32 v20, v0
	v_mul_f32_e32 v0, 0x3fb8aa3b, v17
	v_pk_add_f32 v[12:13], v[12:13], v[16:17]
	v_exp_f32_e32 v21, v0
	s_waitcnt vmcnt(12)
	v_lshlrev_b32_e32 v18, 16, v79
	v_and_b32_e32 v19, 0xffff0000, v79
	v_pk_fma_f32 v[14:15], v[14:15], v[20:21], v[18:19]
	s_waitcnt vmcnt(11)
	v_lshlrev_b32_e32 v16, 16, v48
	v_and_b32_e32 v17, 0xffff0000, v48
	v_mul_f32_e32 v0, 0x3fb8aa3b, v16
	v_exp_f32_e32 v20, v0
	v_mul_f32_e32 v0, 0x3fb8aa3b, v17
	v_pk_add_f32 v[12:13], v[12:13], v[16:17]
	v_exp_f32_e32 v21, v0
	s_waitcnt vmcnt(10)
	v_lshlrev_b32_e32 v18, 16, v80
	v_and_b32_e32 v19, 0xffff0000, v80
	v_pk_fma_f32 v[14:15], v[14:15], v[20:21], v[18:19]
	s_waitcnt vmcnt(9)
	v_lshlrev_b32_e32 v16, 16, v49
	v_and_b32_e32 v17, 0xffff0000, v49
	v_mul_f32_e32 v0, 0x3fb8aa3b, v16
	v_exp_f32_e32 v20, v0
	v_mul_f32_e32 v0, 0x3fb8aa3b, v17
	v_pk_add_f32 v[12:13], v[12:13], v[16:17]
	v_exp_f32_e32 v21, v0
	s_waitcnt vmcnt(8)
	v_lshlrev_b32_e32 v18, 16, v81
	v_and_b32_e32 v19, 0xffff0000, v81
	v_pk_fma_f32 v[14:15], v[14:15], v[20:21], v[18:19]
	s_waitcnt vmcnt(7)
	v_lshlrev_b32_e32 v16, 16, v50
	v_and_b32_e32 v17, 0xffff0000, v50
	v_mul_f32_e32 v0, 0x3fb8aa3b, v16
	v_exp_f32_e32 v20, v0
	v_mul_f32_e32 v0, 0x3fb8aa3b, v17
	v_pk_add_f32 v[12:13], v[12:13], v[16:17]
	v_exp_f32_e32 v21, v0
	s_waitcnt vmcnt(6)
	v_lshlrev_b32_e32 v18, 16, v82
	v_and_b32_e32 v19, 0xffff0000, v82
	v_pk_fma_f32 v[14:15], v[14:15], v[20:21], v[18:19]
	s_waitcnt vmcnt(5)
	v_lshlrev_b32_e32 v16, 16, v51
	v_and_b32_e32 v17, 0xffff0000, v51
	v_mul_f32_e32 v0, 0x3fb8aa3b, v16
	v_exp_f32_e32 v20, v0
	v_mul_f32_e32 v0, 0x3fb8aa3b, v17
	v_pk_add_f32 v[12:13], v[12:13], v[16:17]
	v_exp_f32_e32 v21, v0
	s_waitcnt vmcnt(4)
	v_lshlrev_b32_e32 v18, 16, v83
	v_and_b32_e32 v19, 0xffff0000, v83
	v_pk_fma_f32 v[14:15], v[14:15], v[20:21], v[18:19]
	s_waitcnt vmcnt(3)
	v_lshlrev_b32_e32 v16, 16, v52
	v_and_b32_e32 v17, 0xffff0000, v52
	v_mul_f32_e32 v0, 0x3fb8aa3b, v16
	v_exp_f32_e32 v20, v0
	v_mul_f32_e32 v0, 0x3fb8aa3b, v17
	v_pk_add_f32 v[12:13], v[12:13], v[16:17]
	v_exp_f32_e32 v21, v0
	s_waitcnt vmcnt(2)
	v_lshlrev_b32_e32 v18, 16, v84
	v_and_b32_e32 v19, 0xffff0000, v84
	v_pk_fma_f32 v[14:15], v[14:15], v[20:21], v[18:19]
	s_waitcnt vmcnt(1)
	v_lshlrev_b32_e32 v16, 16, v53
	v_and_b32_e32 v17, 0xffff0000, v53
	v_mul_f32_e32 v0, 0x3fb8aa3b, v16
	v_exp_f32_e32 v20, v0
	v_mul_f32_e32 v0, 0x3fb8aa3b, v17
	v_pk_add_f32 v[12:13], v[12:13], v[16:17]
	v_exp_f32_e32 v21, v0
	s_waitcnt vmcnt(0)
	v_lshlrev_b32_e32 v18, 16, v85
	v_and_b32_e32 v19, 0xffff0000, v85
	v_pk_fma_f32 v[14:15], v[14:15], v[20:21], v[18:19]
	s_sub_i32 s16, s16, 1
	s_cmp_lg_u32 s16, 0
	s_cbranch_scc1 .Llp1_chunk
; DEVI int lbid() { int t = blockIdx.x; asm volatile("" : "+s"(t)); return t; }
; DEVI int lgdim() { int t = gridDim.x; asm volatile("" : "+s"(t)); return t; }
; DEVI void lru_p1_phase(const Params& p) {
;     ...
;   for (int it = lbid(); it < 4 * NCH64B; it += lgdim()) {
;     ...
;     const size_t o = ((size_t)db * NCH64B + pos) * 1024 + ch;
;     *(float2*)(AGP + o) = make_float2(P0, P1); *(float2*)(AGB + o) = make_float2(h0, h1);
;   }
	s_ashr_i32 s16, s23, 31
	s_mul_hi_i32 s15, s22, 0x104
	s_add_u32 s14, s1, s23
	s_addc_u32 s15, s15, s16
	s_lshl_b64 s[14:15], s[14:15], 10
	v_lshl_add_u64 v[8:9], s[14:15], 0, v[2:3]
	v_lshlrev_b64 v[8:9], 2, v[8:9]
	v_lshl_add_u64 v[10:11], s[2:3], 0, v[8:9]
	v_lshl_add_u64 v[8:9], s[12:13], 0, v[8:9]
	s_mov_b32 s1, s50
	global_store_dwordx2 v[10:11], v[12:13], off
	global_store_dwordx2 v[8:9], v[14:15], off
	s_add_i32 s0, s1, s0
	s_cmpk_gt_i32 s0, 0x40f
	s_mov_b32 s80, 0x40000
	s_cbranch_scc0 .LBB0_1141
